# prio
# baseline (speedup 1.0000x reference)
; __device__ __forceinline__ int opaque_tid() { int t = threadIdx.x; asm volatile("" : "+v"(t)); return t; }
; __device__ void phase_proj(const Params& p, char* smem, const XcdBarrier& xb) {
;   const int tid = opaque_tid(), lane = tid & 63, w = tid >> 6, wr = w >> 1, wc = w & 1;
;   char* ws = p.ws;
;   const bf16_t* n1 = (const bf16_t*)(ws + OFF_A);
;   const bf16_t* wt = (const bf16_t*)(ws + OFF_WT_IN);
;   bf16_t* qk = (bf16_t*)(ws + OFF_B);
;   bf16_t* vT = (bf16_t*)(ws + OFF_B_VT);
;   bf16_t* bcx = (bf16_t*)(ws + OFF_B_BCX);
;   f32x4 acc[4][4];
;   DYN_TILE_LOOP(xb, 0, 128, 24, mt, nt) {
.LBB0_157:
	s_or_b64 exec, exec, s[4:5]
	v_mov_b32_e32 v2, v197
	s_lshr_b32 s18, s92, 8
	s_barrier
	s_cmpk_lt_u32 s2, 0x100
	s_cbranch_scc1 .Lprio_skip1
	s_setprio 1
	s_nop 0
.Lprio_skip1:
	s_add_u32 s14, s60, 0xa7a0000
	v_ashrrev_i32_e32 v3, 1, v2
	v_lshrrev_b32_e32 v4, 2, v2
	v_and_b32_e32 v3, 0xffffffc0, v3
	v_and_b32_e32 v4, 12, v4
	v_and_b32_e32 v5, 0x4f, v2
	v_lshl_add_u64 v[192:193], v[0:1], 2, s[62:63]
	s_mov_b64 s[4:5], 0x8000
	s_addc_u32 s15, s61, 0
	v_and_or_b32 v104, v2, 15, v3
	v_or_b32_e32 v105, 0xfffffc00, v5
	v_or_b32_e32 v106, v3, v4
	v_lshl_add_u64 v[96:97], v[192:193], 0, s[4:5]
	v_and_or_b32 v107, v2, 64, v4
	v_mov_b32_e32 v108, 1
	s_movk_i32 s19, 0x70
	v_mov_b32_e32 v99, 0
	s_mov_b32 s28, 0x10000
	s_mov_b32 s29, 0x20000
	s_mov_b32 s30, 0x30000
	s_mov_b32 s7, 0
	s_mov_b32 s31, 0x87a0000
	s_movk_i32 s36, 0x400
	s_movk_i32 s37, 0x7fff
	s_mov_b32 s38, 0xffff0000
	s_mov_b64 s[8:9], 0x60
	v_mov_b32_e32 v109, 0x12010
	s_mov_b32 s6, s91
	s_branch .LBB0_160

; __device__ void phase_chain(const Params& p, char* smem, const XcdBarrier& xb) {
;   char* ws = p.ws;
;   unsigned* bar = xb.bar;
;   const int nloc = __builtin_amdgcn_readfirstlane((int)xb.nloc), xi = __builtin_amdgcn_readfirstlane((int)xb.xi);
;   const int nx = __builtin_amdgcn_readfirstlane((int)xb.nx);
;   const int Mx = (128 - xi + nx - 1) / nx;
;   const int n8 = Mx * 8, total = n8 * 4 + Mx * 16;
;   int L = __builtin_amdgcn_readfirstlane((int)xb.rank);
;   while (L < total) {
.LBB0_311:
	s_or_b64 exec, exec, s[4:5]
	s_cmpk_lt_u32 s35, 0x400
	s_cbranch_scc1 .Lprio_skip2
	s_setprio 1
	s_nop 0
.Lprio_skip2:
	s_abs_i32 s3, s33
	v_cvt_f32_u32_e32 v0, s3
	s_sub_i32 s5, 0, s3
	s_sub_i32 s4, s33, s18
	s_addk_i32 s4, 0x7f
	v_rcp_iflag_f32_e32 v0, v0
	s_xor_b32 s6, s4, s33
	s_abs_i32 s4, s4
	s_ashr_i32 s6, s6, 31
	v_mul_f32_e32 v0, 0x4f7ffffe, v0
	v_cvt_u32_f32_e32 v0, v0
	s_barrier
	v_readfirstlane_b32 s7, v0
	s_mul_i32 s5, s5, s7
	s_mul_hi_u32 s5, s7, s5
	s_add_i32 s7, s7, s5
	s_mul_hi_u32 s5, s4, s7
	s_mul_i32 s7, s5, s3
	s_sub_i32 s4, s4, s7
	s_add_i32 s7, s5, 1
	s_sub_i32 s8, s4, s3
	s_cmp_ge_u32 s4, s3
	s_cselect_b32 s5, s7, s5
	s_cselect_b32 s4, s8, s4
	s_add_i32 s7, s5, 1
	s_cmp_ge_u32 s4, s3
	s_cselect_b32 s3, s7, s5
	s_xor_b32 s3, s3, s6
	s_sub_i32 s4, s3, s6
	s_mul_i32 s3, s4, 48
	s_cmp_ge_i32 s91, s3
	s_mov_b32 s7, 0
	s_cbranch_scc1 .LBB0_463
	s_lshl_b32 s19, s4, 3
	s_lshl_b32 s44, s4, 5
	s_add_u32 s8, s60, 0xe7a0200
	s_addc_u32 s9, s61, 0
	s_add_u32 s45, s60, 0xe00000
	s_addc_u32 s46, s61, 0
	s_add_u32 s10, s60, 0x5790000
	s_addc_u32 s11, s61, 0
	s_add_u32 s24, s60, 0x2480000
	s_addc_u32 s25, s61, 0
	s_add_u32 s47, s60, 0x600000
	s_addc_u32 s49, s61, 0
	s_add_u32 s26, s60, 0xc7a0000
	s_addc_u32 s27, s61, 0
	s_add_u32 s50, s60, 0xd7a0000
	s_addc_u32 s51, s61, 0
	s_add_u32 s52, s60, 0x5580000
	s_addc_u32 s53, s61, 0
	s_add_u32 s28, s60, 0x5680000
	s_addc_u32 s29, s61, 0
	s_add_u32 s54, s60, 0x800000
	s_addc_u32 s55, s61, 0
	s_add_u32 s64, s60, 0x1000000
	s_addc_u32 s65, s61, 0
	s_add_u32 s66, s60, 0x1400000
	s_addc_u32 s67, s61, 0
	s_add_u32 s30, s60, 0x57a0000
	s_addc_u32 s31, s61, 0
	s_abs_i32 s68, s19
	v_cvt_f32_u32_e32 v0, s68
	s_mov_b64 s[4:5], 0xd000
	v_lshl_add_u64 v[102:103], v[192:193], 0, s[4:5]
	s_sub_i32 s4, 0, s68
	v_rcp_iflag_f32_e32 v0, v0
	v_mov_b32_e32 v120, 1
	v_mov_b32_e32 v101, 0
	s_ashr_i32 s69, s19, 31
	v_mul_f32_e32 v0, 0x4f7ffffe, v0
	v_cvt_u32_f32_e32 v0, v0
	s_movk_i32 s71, 0x70
	s_mov_b32 s72, 0x10000
	s_mov_b32 s73, 0x20000
	v_readfirstlane_b32 s5, v0
	s_mul_i32 s4, s4, s5
	s_mul_hi_u32 s4, s5, s4
	v_mbcnt_lo_u32_b32 v0, -1, 0
	s_add_i32 s70, s5, s4
	s_mov_b32 s74, 0x30000
	s_movk_i32 s75, 0xe000
	s_movk_i32 s76, 0x80
	s_movk_i32 s77, 0x7fff
	s_mov_b32 s78, 0x42fe0000
	s_mov_b32 s79, 0xc0c0400
	s_mov_b32 s80, 0x5040100
	s_movk_i32 s81, 0x210
	s_movk_i32 s82, 0x90
	s_movk_i32 s83, 0x840
	v_mov_b32_e32 v121, 0x358637bd
	s_mov_b32 s84, 0x800000
	s_mov_b32 s85, 0x8000
	s_mov_b32 s86, 0x18000
	v_mov_b32_e32 v122, 0x7f7f7f7f
	s_movk_i32 s87, 0x110
	s_movk_i32 s88, 0x204
	s_movk_i32 s89, 0xff80
	v_mov_b32_e32 v123, 0x12010
	v_mbcnt_hi_u32_b32 v124, -1, v0
	v_mov_b32_e32 v125, 0x11400
	v_mov_b32_e32 v194, 0x11800
	v_mov_b32_e32 v195, 0x11408
	v_mov_b32_e32 v196, 0x1140c
	v_mov_b32_e32 v206, 0x11444
	v_mov_b32_e32 v130, 0x11448
	v_mov_b32_e32 v131, 0x1144c
	v_mov_b32_e32 v132, 0x11484
	v_mov_b32_e32 v133, 0x11488
	v_mov_b32_e32 v134, 0x1148c
	v_mov_b32_e32 v135, 0x114c4
	v_mov_b32_e32 v136, 0x114c8
	v_mov_b32_e32 v137, 0x114cc
	v_bfrev_b32_e32 v138, 1
	s_mov_b32 s6, s91
	s_branch .LBB0_314
